# v56 with P6 LN-epilogue pass 1 regenerated too: each step loads 2 row groups x both 64-byte halves of a line (halves back to back), bias/gate math ahead of the wait
# speedup vs baseline: 1.0333x; 1.0093x over previous
;     __device__ __forceinline__ void fused(f32x4 (&acc)[2][2][4][2], const Unit& u, int wr, int wc, int fr, int fq, PG8_LAS unsigned char* lds, int wid, int lane) const {
;     ...
;         const int col0 = u.pn * 256 + wc * 32 + 4 * fq, rowb = u.pm * 256 + wr * 64 + fr;
;         const float* gate = ada + (size_t)((u.pm * 256) >> 11) * 3072 + 2048;
;         int zero = 0; asm volatile("" : "+v"(zero));
;         const float* xp = x + (size_t)(rowb + zero) * D + col0;
;         f32x4 xc[4], xn[4];
; #pragma unroll
;         for (int m = 0; m < 4; ++m) xc[m] = __builtin_nontemporal_load((const f32x4*)(xp + (size_t)(m * 16) * D));
; #pragma unroll
;         for (int g = 0; g < 8; ++g) { const int bj = g >> 2, n = (g >> 1) & 1, ai = g & 1; const int c = col0 + bj * 128 + n * 16;
;             if (g < 7) { const int g1 = g + 1, bj1 = g1 >> 2, n1 = (g1 >> 1) & 1, ai1 = g1 & 1;
; #pragma unroll
;                 for (int m = 0; m < 4; ++m) xn[m] = __builtin_nontemporal_load((const f32x4*)(xp + (size_t)(ai1 * 128 + m * 16) * D + bj1 * 128 + n1 * 16)); }
;             const f32x4 gv = *(const f32x4*)(gate + c), bv = *(const f32x4*)(bo + c);
;             asm volatile("" ::: "memory");
; #pragma unroll
;             for (int m = 0; m < 4; ++m) acc[ai][bj][m][n] = xc[m] * ALPHA + gv * (acc[ai][bj][m][n] + bv);
;             asm volatile("" : "+v"(acc[ai][bj][0][n]), "+v"(acc[ai][bj][1][n]), "+v"(acc[ai][bj][2][n]), "+v"(acc[ai][bj][3][n]));
;             asm volatile("" ::: "memory");
; #pragma unroll
;             for (int m = 0; m < 4; ++m) xc[m] = xn[m]; }
.LBB0_496:
	s_lshl_b32 s0, s39, 5
	s_lshl_b32 s1, s4, 8
	s_or_b32 s0, s1, s0
	v_lshrrev_b32_e32 v128, 2, v174
	v_and_or_b32 v166, v128, 12, s0
	s_lshl_b32 s6, s38, 8
	v_mov_b32_e32 v128, v149
	s_barrier
	v_add_u32_e32 v152, s6, v153
	v_add_u32_e32 v128, v128, v152
	v_ashrrev_i32_e32 v129, 31, v128
	v_lshlrev_b64 v[128:129], 12, v[128:129]
	v_ashrrev_i32_e32 v167, 31, v166
	s_ashr_i32 s0, s38, 3
	v_lshlrev_b64 v[154:155], 2, v[166:167]
	v_lshl_add_u64 v[128:129], s[76:77], 0, v[128:129]
	s_mul_hi_i32 s1, s0, 0x3000
	s_mulk_i32 s0, 0x3000
	v_lshl_add_u64 v[140:141], v[128:129], 0, v[154:155]
	s_add_u32 s0, s96, s0
	v_add_co_u32_e32 v136, vcc, s51, v140
	s_addc_u32 s1, s97, s1
	v_readlane_b32 s60, v250, 0
	v_addc_co_u32_e32 v137, vcc, 0, v141, vcc
	v_readlane_b32 s64, v250, 4
	v_readlane_b32 s65, v250, 5
	s_add_u32 s0, s0, 0x2000
	v_add_co_u32_e32 v128, vcc, s52, v140
	v_lshl_add_u64 v[156:157], s[64:65], 0, v[154:155]
	s_addc_u32 s1, s1, 0
	v_addc_co_u32_e32 v129, vcc, 0, v141, vcc
	global_load_dwordx4 v[216:219], v[156:157], off
	global_load_dwordx4 v[220:223], v[156:157], off offset:64
	global_load_dwordx4 v[224:227], v[156:157], off offset:512
	global_load_dwordx4 v[228:231], v[156:157], off offset:576
	v_lshl_add_u64 v[138:139], s[0:1], 0, v[154:155]
	v_add_co_u32_e32 v130, vcc, s53, v140
	global_load_dwordx4 v[232:235], v[138:139], off
	global_load_dwordx4 v[236:239], v[138:139], off offset:64
	global_load_dwordx4 v[240:243], v[138:139], off offset:512
	global_load_dwordx4 v[244:247], v[138:139], off offset:576
	s_nop 0
	v_addc_co_u32_e32 v131, vcc, 0, v141, vcc
	v_add_co_u32_e32 v158, vcc, s54, v140
	v_xor_b32_e32 v148, 16, v172
	s_nop 0
	v_addc_co_u32_e32 v159, vcc, 0, v141, vcc
	v_add_co_u32_e32 v160, vcc, s55, v140
	v_readlane_b32 s61, v250, 1
	s_nop 0
	v_addc_co_u32_e32 v161, vcc, 0, v141, vcc
	v_add_co_u32_e32 v162, vcc, s56, v140
	v_readlane_b32 s62, v250, 2
	s_nop 0
	v_addc_co_u32_e32 v163, vcc, 0, v141, vcc
	v_add_co_u32_e32 v164, vcc, s57, v140
	v_readlane_b32 s63, v250, 3
	s_nop 0
	v_addc_co_u32_e32 v165, vcc, 0, v141, vcc
	v_readlane_b32 s66, v250, 6
	v_readlane_b32 s67, v250, 7
	global_load_dwordx4 v[180:183], v[140:141], off nt
	global_load_dwordx4 v[184:187], v[140:141], off offset:64 nt
	global_load_dwordx4 v[188:191], v[136:137], off nt
	global_load_dwordx4 v[192:195], v[136:137], off offset:64 nt
	global_load_dwordx4 v[196:199], v[128:129], off nt
	global_load_dwordx4 v[200:203], v[128:129], off offset:64 nt
	global_load_dwordx4 v[204:207], v[130:131], off nt
	global_load_dwordx4 v[208:211], v[130:131], off offset:64 nt
	s_waitcnt vmcnt(8)
	v_pk_add_f32 v[80:81], v[80:81], v[216:217]
	v_pk_add_f32 v[82:83], v[82:83], v[218:219]
	v_pk_add_f32 v[84:85], v[84:85], v[220:221]
	v_pk_add_f32 v[86:87], v[86:87], v[222:223]
	v_pk_add_f32 v[76:77], v[76:77], v[216:217]
	v_pk_add_f32 v[78:79], v[78:79], v[218:219]
	v_pk_add_f32 v[52:53], v[52:53], v[220:221]
	v_pk_add_f32 v[54:55], v[54:55], v[222:223]
	v_pk_mul_f32 v[80:81], v[232:233], v[80:81]
	v_pk_mul_f32 v[82:83], v[234:235], v[82:83]
	v_pk_mul_f32 v[84:85], v[236:237], v[84:85]
	v_pk_mul_f32 v[86:87], v[238:239], v[86:87]
	v_pk_mul_f32 v[76:77], v[232:233], v[76:77]
	v_pk_mul_f32 v[78:79], v[234:235], v[78:79]
	v_pk_mul_f32 v[52:53], v[236:237], v[52:53]
	v_pk_mul_f32 v[54:55], v[238:239], v[54:55]
	s_waitcnt vmcnt(4)
	v_pk_fma_f32 v[80:81], v[180:181], s[34:35], v[80:81] op_sel_hi:[1,0,1]
	v_pk_fma_f32 v[82:83], v[182:183], s[34:35], v[82:83] op_sel_hi:[1,0,1]
	v_pk_fma_f32 v[84:85], v[184:185], s[34:35], v[84:85] op_sel_hi:[1,0,1]
	v_pk_fma_f32 v[86:87], v[186:187], s[34:35], v[86:87] op_sel_hi:[1,0,1]
	v_pk_fma_f32 v[76:77], v[188:189], s[34:35], v[76:77] op_sel_hi:[1,0,1]
	v_pk_fma_f32 v[78:79], v[190:191], s[34:35], v[78:79] op_sel_hi:[1,0,1]
	v_pk_fma_f32 v[52:53], v[192:193], s[34:35], v[52:53] op_sel_hi:[1,0,1]
	v_pk_fma_f32 v[54:55], v[194:195], s[34:35], v[54:55] op_sel_hi:[1,0,1]
	global_load_dwordx4 v[180:183], v[158:159], off nt
	global_load_dwordx4 v[184:187], v[158:159], off offset:64 nt
	global_load_dwordx4 v[188:191], v[160:161], off nt
	global_load_dwordx4 v[192:195], v[160:161], off offset:64 nt
	v_pk_add_f32 v[64:65], v[64:65], v[216:217]
	v_pk_add_f32 v[66:67], v[66:67], v[218:219]
	v_pk_add_f32 v[32:33], v[32:33], v[220:221]
	v_pk_add_f32 v[34:35], v[34:35], v[222:223]
	v_pk_add_f32 v[60:61], v[60:61], v[216:217]
	v_pk_add_f32 v[62:63], v[62:63], v[218:219]
	v_pk_add_f32 v[16:17], v[16:17], v[220:221]
	v_pk_add_f32 v[18:19], v[18:19], v[222:223]
	v_pk_mul_f32 v[64:65], v[232:233], v[64:65]
	v_pk_mul_f32 v[66:67], v[234:235], v[66:67]
	v_pk_mul_f32 v[32:33], v[236:237], v[32:33]
	v_pk_mul_f32 v[34:35], v[238:239], v[34:35]
	v_pk_mul_f32 v[132:133], v[232:233], v[60:61]
	v_pk_mul_f32 v[134:135], v[234:235], v[62:63]
	v_pk_mul_f32 v[16:17], v[236:237], v[16:17]
	v_pk_mul_f32 v[18:19], v[238:239], v[18:19]
	s_waitcnt vmcnt(4)
;     __device__ __forceinline__ void fused(f32x4 (&acc)[2][2][4][2], const Unit& u, int wr, int wc, int fr, int fq, PG8_LAS unsigned char* lds, int wid, int lane) const {
;     ...
;         const int col0 = u.pn * 256 + wc * 32 + 4 * fq, rowb = u.pm * 256 + wr * 64 + fr;
;         const float* gate = ada + (size_t)((u.pm * 256) >> 11) * 3072 + 2048;
;         int zero = 0; asm volatile("" : "+v"(zero));
;         const float* xp = x + (size_t)(rowb + zero) * D + col0;
;         f32x4 xc[4], xn[4];
; #pragma unroll
;         for (int m = 0; m < 4; ++m) xc[m] = __builtin_nontemporal_load((const f32x4*)(xp + (size_t)(m * 16) * D));
; #pragma unroll
;         for (int g = 0; g < 8; ++g) { const int bj = g >> 2, n = (g >> 1) & 1, ai = g & 1; const int c = col0 + bj * 128 + n * 16;
;             if (g < 7) { const int g1 = g + 1, bj1 = g1 >> 2, n1 = (g1 >> 1) & 1, ai1 = g1 & 1;
; #pragma unroll
;                 for (int m = 0; m < 4; ++m) xn[m] = __builtin_nontemporal_load((const f32x4*)(xp + (size_t)(ai1 * 128 + m * 16) * D + bj1 * 128 + n1 * 16)); }
;             const f32x4 gv = *(const f32x4*)(gate + c), bv = *(const f32x4*)(bo + c);
;             asm volatile("" ::: "memory");
; #pragma unroll
;             for (int m = 0; m < 4; ++m) acc[ai][bj][m][n] = xc[m] * ALPHA + gv * (acc[ai][bj][m][n] + bv);
;             asm volatile("" : "+v"(acc[ai][bj][0][n]), "+v"(acc[ai][bj][1][n]), "+v"(acc[ai][bj][2][n]), "+v"(acc[ai][bj][3][n]));
;             asm volatile("" ::: "memory");
; #pragma unroll
;             for (int m = 0; m < 4; ++m) xc[m] = xn[m]; }
	v_pk_fma_f32 v[60:61], v[196:197], s[34:35], v[64:65] op_sel_hi:[1,0,1]
	v_pk_fma_f32 v[62:63], v[198:199], s[34:35], v[66:67] op_sel_hi:[1,0,1]
	v_pk_fma_f32 v[32:33], v[200:201], s[34:35], v[32:33] op_sel_hi:[1,0,1]
	v_pk_fma_f32 v[34:35], v[202:203], s[34:35], v[34:35] op_sel_hi:[1,0,1]
	v_pk_fma_f32 v[64:65], v[204:205], s[34:35], v[132:133] op_sel_hi:[1,0,1]
	v_pk_fma_f32 v[66:67], v[206:207], s[34:35], v[134:135] op_sel_hi:[1,0,1]
	v_pk_fma_f32 v[16:17], v[208:209], s[34:35], v[16:17] op_sel_hi:[1,0,1]
	v_pk_fma_f32 v[18:19], v[210:211], s[34:35], v[18:19] op_sel_hi:[1,0,1]
	global_load_dwordx4 v[196:199], v[162:163], off nt
	global_load_dwordx4 v[200:203], v[162:163], off offset:64 nt
	global_load_dwordx4 v[204:207], v[164:165], off nt
	global_load_dwordx4 v[208:211], v[164:165], off offset:64 nt
	v_pk_add_f32 v[28:29], v[28:29], v[216:217]
	v_pk_add_f32 v[30:31], v[30:31], v[218:219]
	v_pk_add_f32 v[8:9], v[8:9], v[220:221]
	v_pk_add_f32 v[10:11], v[10:11], v[222:223]
	v_pk_add_f32 v[44:45], v[44:45], v[216:217]
	v_pk_add_f32 v[46:47], v[46:47], v[218:219]
	v_pk_add_f32 v[24:25], v[24:25], v[220:221]
	v_pk_add_f32 v[26:27], v[26:27], v[222:223]
	v_pk_mul_f32 v[28:29], v[232:233], v[28:29]
	v_pk_mul_f32 v[30:31], v[234:235], v[30:31]
	v_pk_mul_f32 v[8:9], v[236:237], v[8:9]
	v_pk_mul_f32 v[10:11], v[238:239], v[10:11]
	v_pk_mul_f32 v[44:45], v[232:233], v[44:45]
	v_pk_mul_f32 v[46:47], v[234:235], v[46:47]
	v_pk_mul_f32 v[24:25], v[236:237], v[24:25]
	v_pk_mul_f32 v[26:27], v[238:239], v[26:27]
	s_waitcnt vmcnt(4)
	v_pk_fma_f32 v[28:29], v[180:181], s[34:35], v[28:29] op_sel_hi:[1,0,1]
	v_pk_fma_f32 v[30:31], v[182:183], s[34:35], v[30:31] op_sel_hi:[1,0,1]
	v_pk_fma_f32 v[8:9], v[184:185], s[34:35], v[8:9] op_sel_hi:[1,0,1]
	v_pk_fma_f32 v[10:11], v[186:187], s[34:35], v[10:11] op_sel_hi:[1,0,1]
	v_pk_fma_f32 v[44:45], v[188:189], s[34:35], v[44:45] op_sel_hi:[1,0,1]
	v_pk_fma_f32 v[46:47], v[190:191], s[34:35], v[46:47] op_sel_hi:[1,0,1]
	v_pk_fma_f32 v[24:25], v[192:193], s[34:35], v[24:25] op_sel_hi:[1,0,1]
	v_pk_fma_f32 v[26:27], v[194:195], s[34:35], v[26:27] op_sel_hi:[1,0,1]
	global_load_dwordx4 v[180:183], v[140:141], off offset:512 nt
	global_load_dwordx4 v[184:187], v[140:141], off offset:576 nt
	global_load_dwordx4 v[188:191], v[136:137], off offset:512 nt
	global_load_dwordx4 v[192:195], v[136:137], off offset:576 nt
	v_pk_add_f32 v[88:89], v[88:89], v[216:217]
	v_pk_add_f32 v[90:91], v[90:91], v[218:219]
	v_pk_add_f32 v[48:49], v[48:49], v[220:221]
	v_pk_add_f32 v[50:51], v[50:51], v[222:223]
	v_pk_add_f32 v[92:93], v[92:93], v[216:217]
	v_pk_add_f32 v[94:95], v[94:95], v[218:219]
	v_pk_add_f32 v[68:69], v[68:69], v[220:221]
	v_pk_add_f32 v[70:71], v[70:71], v[222:223]
	v_pk_mul_f32 v[88:89], v[232:233], v[88:89]
	v_pk_mul_f32 v[90:91], v[234:235], v[90:91]
	v_pk_mul_f32 v[48:49], v[236:237], v[48:49]
	v_pk_mul_f32 v[50:51], v[238:239], v[50:51]
	v_pk_mul_f32 v[92:93], v[232:233], v[92:93]
	v_pk_mul_f32 v[94:95], v[234:235], v[94:95]
	v_pk_mul_f32 v[68:69], v[236:237], v[68:69]
	v_pk_mul_f32 v[70:71], v[238:239], v[70:71]
	s_waitcnt vmcnt(4)
	v_pk_fma_f32 v[88:89], v[196:197], s[34:35], v[88:89] op_sel_hi:[1,0,1]
	v_pk_fma_f32 v[90:91], v[198:199], s[34:35], v[90:91] op_sel_hi:[1,0,1]
	v_pk_fma_f32 v[48:49], v[200:201], s[34:35], v[48:49] op_sel_hi:[1,0,1]
	v_pk_fma_f32 v[50:51], v[202:203], s[34:35], v[50:51] op_sel_hi:[1,0,1]
	v_pk_fma_f32 v[92:93], v[204:205], s[34:35], v[92:93] op_sel_hi:[1,0,1]
	v_pk_fma_f32 v[94:95], v[206:207], s[34:35], v[94:95] op_sel_hi:[1,0,1]
	v_pk_fma_f32 v[68:69], v[208:209], s[34:35], v[68:69] op_sel_hi:[1,0,1]
	v_pk_fma_f32 v[70:71], v[210:211], s[34:35], v[70:71] op_sel_hi:[1,0,1]
	global_load_dwordx4 v[196:199], v[128:129], off offset:512 nt
	global_load_dwordx4 v[200:203], v[128:129], off offset:576 nt
	global_load_dwordx4 v[204:207], v[130:131], off offset:512 nt
	global_load_dwordx4 v[208:211], v[130:131], off offset:576 nt
	v_pk_add_f32 v[72:73], v[72:73], v[224:225]
	v_pk_add_f32 v[74:75], v[74:75], v[226:227]
	v_pk_add_f32 v[116:117], v[116:117], v[228:229]
	v_pk_add_f32 v[118:119], v[118:119], v[230:231]
	v_pk_add_f32 v[40:41], v[40:41], v[224:225]
	v_pk_add_f32 v[42:43], v[42:43], v[226:227]
	v_pk_add_f32 v[108:109], v[108:109], v[228:229]
	v_pk_add_f32 v[110:111], v[110:111], v[230:231]
	v_pk_mul_f32 v[72:73], v[240:241], v[72:73]
	v_pk_mul_f32 v[74:75], v[242:243], v[74:75]
	v_pk_mul_f32 v[116:117], v[244:245], v[116:117]
	v_pk_mul_f32 v[118:119], v[246:247], v[118:119]
	v_pk_mul_f32 v[40:41], v[240:241], v[40:41]
	v_pk_mul_f32 v[42:43], v[242:243], v[42:43]
	v_pk_mul_f32 v[108:109], v[244:245], v[108:109]
	v_pk_mul_f32 v[110:111], v[246:247], v[110:111]
	s_waitcnt vmcnt(4)
	v_pk_fma_f32 v[72:73], v[180:181], s[34:35], v[72:73] op_sel_hi:[1,0,1]
	v_pk_fma_f32 v[74:75], v[182:183], s[34:35], v[74:75] op_sel_hi:[1,0,1]
	v_pk_fma_f32 v[116:117], v[184:185], s[34:35], v[116:117] op_sel_hi:[1,0,1]
	v_pk_fma_f32 v[118:119], v[186:187], s[34:35], v[118:119] op_sel_hi:[1,0,1]
	v_pk_fma_f32 v[40:41], v[188:189], s[34:35], v[40:41] op_sel_hi:[1,0,1]
	v_pk_fma_f32 v[42:43], v[190:191], s[34:35], v[42:43] op_sel_hi:[1,0,1]
	v_pk_fma_f32 v[108:109], v[192:193], s[34:35], v[108:109] op_sel_hi:[1,0,1]
	v_pk_fma_f32 v[110:111], v[194:195], s[34:35], v[110:111] op_sel_hi:[1,0,1]
	global_load_dwordx4 v[180:183], v[158:159], off offset:512 nt
	global_load_dwordx4 v[184:187], v[158:159], off offset:576 nt
	global_load_dwordx4 v[188:191], v[160:161], off offset:512 nt
	global_load_dwordx4 v[192:195], v[160:161], off offset:576 nt
	v_pk_add_f32 v[20:21], v[20:21], v[224:225]
	v_pk_add_f32 v[22:23], v[22:23], v[226:227]
	v_pk_add_f32 v[100:101], v[100:101], v[228:229]
	v_pk_add_f32 v[102:103], v[102:103], v[230:231]
	v_pk_add_f32 v[4:5], v[4:5], v[224:225]
	v_pk_add_f32 v[6:7], v[6:7], v[226:227]
	v_pk_add_f32 v[96:97], v[96:97], v[228:229]
	v_pk_add_f32 v[98:99], v[98:99], v[230:231]
	v_pk_mul_f32 v[20:21], v[240:241], v[20:21]
	v_pk_mul_f32 v[22:23], v[242:243], v[22:23]
	v_pk_mul_f32 v[100:101], v[244:245], v[100:101]
	v_pk_mul_f32 v[102:103], v[246:247], v[102:103]
	v_pk_mul_f32 v[4:5], v[240:241], v[4:5]
	v_pk_mul_f32 v[6:7], v[242:243], v[6:7]
	v_pk_mul_f32 v[96:97], v[244:245], v[96:97]
	v_pk_mul_f32 v[98:99], v[246:247], v[98:99]
	s_waitcnt vmcnt(4)
;     __device__ __forceinline__ bool run(const f32x4 (&v)[2][2][4][2], const Unit& u, int wr, int wc, int fr, int fq, PG8_LAS unsigned char* lds, int wid, int lane) const {
;     ...
;                     for (int n = 0; n < 2; ++n) { const f32x4 x = v[ai][bj][m][n]; s += (x[0] + x[1]) + (x[2] + x[3]); }
;                 s += __shfl_xor(s, 16); s += __shfl_xor(s, 32);
;                 const float mw = s * (1.0f / 64.0f); float q = 0.f;
;     __device__ __forceinline__ void fused(f32x4 (&acc)[2][2][4][2], const Unit& u, int wr, int wc, int fr, int fq, PG8_LAS unsigned char* lds, int wid, int lane) const {
;     ...
;             for (int m = 0; m < 4; ++m) acc[ai][bj][m][n] = xc[m] * ALPHA + gv * (acc[ai][bj][m][n] + bv);
	v_pk_fma_f32 v[20:21], v[196:197], s[34:35], v[20:21] op_sel_hi:[1,0,1]
	v_pk_fma_f32 v[22:23], v[198:199], s[34:35], v[22:23] op_sel_hi:[1,0,1]
	v_pk_fma_f32 v[100:101], v[200:201], s[34:35], v[100:101] op_sel_hi:[1,0,1]
	v_pk_fma_f32 v[102:103], v[202:203], s[34:35], v[102:103] op_sel_hi:[1,0,1]
	v_pk_fma_f32 v[4:5], v[204:205], s[34:35], v[4:5] op_sel_hi:[1,0,1]
	v_pk_fma_f32 v[6:7], v[206:207], s[34:35], v[6:7] op_sel_hi:[1,0,1]
	v_pk_fma_f32 v[96:97], v[208:209], s[34:35], v[96:97] op_sel_hi:[1,0,1]
	v_pk_fma_f32 v[98:99], v[210:211], s[34:35], v[98:99] op_sel_hi:[1,0,1]
	global_load_dwordx4 v[196:199], v[162:163], off offset:512 nt
	global_load_dwordx4 v[200:203], v[162:163], off offset:576 nt
	global_load_dwordx4 v[204:207], v[164:165], off offset:512 nt
	global_load_dwordx4 v[208:211], v[164:165], off offset:576 nt
	v_pk_add_f32 v[0:1], v[0:1], v[224:225]
	v_pk_add_f32 v[2:3], v[2:3], v[226:227]
	v_pk_add_f32 v[104:105], v[104:105], v[228:229]
	v_pk_add_f32 v[106:107], v[106:107], v[230:231]
	v_pk_add_f32 v[12:13], v[12:13], v[224:225]
	v_pk_add_f32 v[14:15], v[14:15], v[226:227]
	v_pk_add_f32 v[112:113], v[112:113], v[228:229]
	v_pk_add_f32 v[114:115], v[114:115], v[230:231]
	v_pk_mul_f32 v[0:1], v[240:241], v[0:1]
	v_pk_mul_f32 v[2:3], v[242:243], v[2:3]
	v_pk_mul_f32 v[104:105], v[244:245], v[104:105]
	v_pk_mul_f32 v[106:107], v[246:247], v[106:107]
	v_pk_mul_f32 v[12:13], v[240:241], v[12:13]
	v_pk_mul_f32 v[14:15], v[242:243], v[14:15]
	v_pk_mul_f32 v[112:113], v[244:245], v[112:113]
	v_pk_mul_f32 v[114:115], v[246:247], v[114:115]
	s_waitcnt vmcnt(4)
	v_pk_fma_f32 v[0:1], v[180:181], s[34:35], v[0:1] op_sel_hi:[1,0,1]
	v_pk_fma_f32 v[2:3], v[182:183], s[34:35], v[2:3] op_sel_hi:[1,0,1]
	v_pk_fma_f32 v[104:105], v[184:185], s[34:35], v[104:105] op_sel_hi:[1,0,1]
	v_pk_fma_f32 v[106:107], v[186:187], s[34:35], v[106:107] op_sel_hi:[1,0,1]
	v_pk_fma_f32 v[12:13], v[188:189], s[34:35], v[12:13] op_sel_hi:[1,0,1]
	v_pk_fma_f32 v[14:15], v[190:191], s[34:35], v[14:15] op_sel_hi:[1,0,1]
	v_pk_fma_f32 v[112:113], v[192:193], s[34:35], v[112:113] op_sel_hi:[1,0,1]
	v_pk_fma_f32 v[114:115], v[194:195], s[34:35], v[114:115] op_sel_hi:[1,0,1]
	v_pk_add_f32 v[36:37], v[36:37], v[224:225]
	v_pk_add_f32 v[38:39], v[38:39], v[226:227]
	v_pk_add_f32 v[120:121], v[120:121], v[228:229]
	v_pk_add_f32 v[122:123], v[122:123], v[230:231]
	v_pk_add_f32 v[56:57], v[56:57], v[224:225]
	v_pk_add_f32 v[58:59], v[58:59], v[226:227]
	v_pk_add_f32 v[124:125], v[124:125], v[228:229]
	v_pk_add_f32 v[126:127], v[126:127], v[230:231]
	v_pk_mul_f32 v[36:37], v[240:241], v[36:37]
	v_pk_mul_f32 v[38:39], v[242:243], v[38:39]
	v_pk_mul_f32 v[120:121], v[244:245], v[120:121]
	v_pk_mul_f32 v[122:123], v[246:247], v[122:123]
	v_pk_mul_f32 v[56:57], v[240:241], v[56:57]
	v_pk_mul_f32 v[58:59], v[242:243], v[58:59]
	v_pk_mul_f32 v[124:125], v[244:245], v[124:125]
	v_pk_mul_f32 v[126:127], v[246:247], v[126:127]
	s_waitcnt vmcnt(0)
	v_pk_fma_f32 v[36:37], v[196:197], s[34:35], v[36:37] op_sel_hi:[1,0,1]
	v_pk_fma_f32 v[38:39], v[198:199], s[34:35], v[38:39] op_sel_hi:[1,0,1]
	v_pk_fma_f32 v[120:121], v[200:201], s[34:35], v[120:121] op_sel_hi:[1,0,1]
	v_pk_fma_f32 v[122:123], v[202:203], s[34:35], v[122:123] op_sel_hi:[1,0,1]
	v_pk_fma_f32 v[56:57], v[204:205], s[34:35], v[56:57] op_sel_hi:[1,0,1]
	v_pk_fma_f32 v[58:59], v[206:207], s[34:35], v[58:59] op_sel_hi:[1,0,1]
	v_pk_fma_f32 v[124:125], v[208:209], s[34:35], v[124:125] op_sel_hi:[1,0,1]
	v_pk_fma_f32 v[126:127], v[210:211], s[34:35], v[126:127] op_sel_hi:[1,0,1]
	v_and_b32_e32 v166, 64, v172
	v_mov_b32_e32 v194, v81
	v_mov_b32_e32 v195, v82
	s_lshl_b32 s0, s39, 3
	s_add_i32 s7, s0, 0
	v_add_u32_e32 v198, 64, v166
	v_mov_b32_e32 v196, v80
	v_mov_b32_e32 v197, v83
	v_cmp_lt_i32_e32 vcc, v148, v198
	v_mov_b32_e32 v130, v85
	v_mov_b32_e32 v131, v86
	v_mov_b32_e32 v132, v84
	v_mov_b32_e32 v133, v87
	v_pk_add_f32 v[128:129], v[194:195], v[196:197]
	v_pk_add_f32 v[130:131], v[130:131], v[132:133]
	v_add_f32_e32 v128, v128, v129
	v_pk_add_f32 v[130:131], v[130:131], v[130:131] op_sel:[0,1] op_sel_hi:[1,0]
	v_add_f32_e32 v128, 0, v128
	v_add_f32_e32 v132, v72, v73
	v_add_f32_e32 v142, v74, v75
	v_mov_b32_e32 v129, v116
	v_mov_b32_e32 v131, v117
	v_mov_b32_e32 v133, v118
	v_mov_b32_e32 v143, v119
	v_pk_add_f32 v[128:129], v[128:129], v[130:131]
	v_pk_add_f32 v[130:131], v[132:133], v[142:143]
	v_cndmask_b32_e32 v148, v172, v148, vcc
	v_pk_add_f32 v[128:129], v[128:129], v[130:131]
	v_lshlrev_b32_e32 v148, 2, v148
	v_add_f32_e32 v129, v128, v129
	v_mov_b32_e32 v130, v129
	v_mov_b32_e32 v212, v129
	s_nop 1
	v_permlane16_swap_b32_e32 v130, v212
	v_xor_b32_e32 v128, 32, v172
	v_cmp_lt_i32_e32 vcc, v128, v198
	s_waitcnt lgkmcnt(0)
	v_add_f32_e32 v129, v130, v212
	v_cndmask_b32_e32 v128, v172, v128, vcc
	v_lshlrev_b32_e32 v128, 2, v128
	v_mov_b32_e32 v130, v129
	v_mov_b32_e32 v212, v129
	s_nop 1
	v_permlane32_swap_b32_e32 v130, v212
	s_waitcnt lgkmcnt(0)
	v_add_f32_e32 v129, v130, v212
	v_fmamk_f32 v131, v129, 0xbc800000, v83
	v_fmamk_f32 v133, v129, 0xbc800000, v81
	v_fmamk_f32 v143, v129, 0xbc800000, v87
	v_fmamk_f32 v157, v129, 0xbc800000, v85
	v_fmamk_f32 v130, v129, 0xbc800000, v82
	v_fmamk_f32 v132, v129, 0xbc800000, v80
	v_fmamk_f32 v142, v129, 0xbc800000, v86
	v_fmamk_f32 v156, v129, 0xbc800000, v84
	v_fmamk_f32 v159, v129, 0xbc800000, v75
	v_fmamk_f32 v177, v129, 0xbc800000, v73
	v_mul_f32_e32 v133, v133, v133
	v_mul_f32_e32 v131, v131, v131
	v_mul_f32_e32 v157, v157, v157
	v_mul_f32_e32 v143, v143, v143
	v_fmamk_f32 v158, v129, 0xbc800000, v74
	v_fmamk_f32 v176, v129, 0xbc800000, v72
	v_fmamk_f32 v179, v129, 0xbc800000, v119
	v_fmamk_f32 v181, v129, 0xbc800000, v117
	v_mul_f32_e32 v177, v177, v177
	v_mul_f32_e32 v159, v159, v159
	v_fmac_f32_e32 v133, v132, v132
	v_fmac_f32_e32 v131, v130, v130
	v_fmac_f32_e32 v157, v156, v156
	v_fmac_f32_e32 v143, v142, v142
	v_fmamk_f32 v178, v129, 0xbc800000, v118
	v_fmamk_f32 v180, v129, 0xbc800000, v116
	v_mul_f32_e32 v181, v181, v181
	v_mul_f32_e32 v179, v179, v179
	v_fmac_f32_e32 v177, v176, v176
	v_fmac_f32_e32 v159, v158, v158
	v_add_f32_e32 v130, v133, v131
	v_add_f32_e32 v131, v157, v143
	v_fmac_f32_e32 v181, v180, v180
	v_fmac_f32_e32 v179, v178, v178
	v_add_f32_e32 v132, v177, v159
	v_add_f32_e32 v130, v130, v131
	v_add_f32_e32 v133, v181, v179
	v_add_f32_e32 v130, v132, v130
	v_add_f32_e32 v131, v133, v130
	v_mov_b32_e32 v132, v131
	v_mov_b32_e32 v212, v131
	s_nop 1
	v_permlane16_swap_b32_e32 v132, v212
	v_and_b32_e32 v130, 63, v174
	v_cmp_gt_u32_e32 vcc, 16, v130
	s_waitcnt lgkmcnt(0)
	v_add_f32_e32 v131, v132, v212
	v_mov_b32_e32 v132, v131
	v_mov_b32_e32 v212, v131
	s_nop 1
	v_permlane32_swap_b32_e32 v132, v212
	s_nop 0
	s_and_saveexec_b64 s[0:1], vcc
	s_cbranch_execz .LBB0_498
	s_lshl_b32 s39, s59, 11
	s_add_i32 s39, s7, s39
	v_mul_f32_e32 v134, 0x3c800000, v129
	v_lshl_add_u32 v129, v175, 5, s39
	s_waitcnt lgkmcnt(0)
	v_add_f32_e32 v135, v132, v212
	ds_write_b64 v129, v[134:135]
